# ph3 epilogue: kvs/kvw bf16 K/V copies also stored 16 bytes per lane (permlane16_swap pairing)
# speedup vs baseline: 1.0194x; 1.0003x over previous
.LBB0_362:
	v_ashrrev_i32_e32 v157, 31, v156
	s_movk_i32 s0, 0x5ff
	v_cmp_lt_u32_e64 s[0:1], s0, v165
	v_ashrrev_i32_e32 v163, 31, v162
	v_lshlrev_b32_e32 v191, 9, v165
	v_lshlrev_b32_e32 v166, 11, v165
	v_lshlrev_b64 v[170:171], 9, v[156:157]
	s_mov_b64 s[8:9], 0x2a00000
	v_ashrrev_i32_e32 v165, 31, v164
	v_lshlrev_b64 v[168:169], 20, v[162:163]
	v_lshl_add_u64 v[162:163], v[170:171], 0, s[8:9]
	v_lshlrev_b64 v[172:173], 9, v[164:165]
	s_mov_b64 s[8:9], 0x349e000
	v_lshlrev_b64 v[160:161], 10, v[156:157]
	v_lshl_add_u64 v[164:165], v[172:173], 0, s[8:9]
	v_or_b32_e32 v157, s45, v140
	s_mov_b64 s[8:9], -1
	s_and_b64 vcc, exec, s[54:55]
	s_cbranch_vccz .LBB0_375
	s_and_b64 vcc, exec, s[56:57]
	s_cbranch_vccz .LBB0_371
	s_and_b64 vcc, exec, s[52:53]
	s_cbranch_vccz .LBB0_368
	v_lshl_add_u64 v[192:193], s[22:23], 0, v[160:161]
	v_lshlrev_b32_e32 v194, 1, v157
	v_mov_b32_e32 v195, v139
	v_lshl_add_u64 v[192:193], v[192:193], 0, v[194:195]
	v_cvt_pk_bf16_f32 v216, v130, v131
	v_cvt_pk_bf16_f32 v217, v132, v133
	s_and_saveexec_b64 s[8:9], s[0:1]
	s_cbranch_execz .LBB0_367
	v_readlane_b32 s62, v253, 45
	v_readlane_b32 s63, v253, 46
	v_lshlrev_b32_e32 v194, 2, v191
	v_mov_b32_e32 v195, v139
	v_lshl_add_u64 v[192:193], s[62:63], 0, v[168:169]
	v_lshl_add_u64 v[192:193], v[192:193], 0, v[194:195]
	v_lshlrev_b32_e32 v194, 2, v157
	v_lshl_add_u64 v[192:193], v[192:193], 0, v[194:195]
	global_store_dwordx4 v[192:193], v[130:133], off

.LBB0_371:
	s_andn2_b64 vcc, exec, s[8:9]
	s_cbranch_vccnz .LBB0_374
	v_cndmask_b32_e64 v193, v163, v165, s[6:7]
	v_cndmask_b32_e64 v192, v162, v164, s[6:7]
	v_lshl_add_u64 v[192:193], v[192:193], 2, s[90:91]
	v_lshlrev_b32_e32 v194, 2, v157
	v_mov_b32_e32 v195, v139
	v_lshl_add_u64 v[192:193], v[192:193], 0, v[194:195]
	s_andn2_b64 vcc, exec, s[52:53]
	global_store_dwordx4 v[192:193], v[130:133], off
	s_cbranch_vccnz .LBB0_374
	v_lshl_add_u64 v[192:193], s[20:21], 0, v[160:161]
	v_lshlrev_b32_e32 v194, 1, v157
	v_mov_b32_e32 v195, v139
	v_lshl_add_u64 v[192:193], v[192:193], 0, v[194:195]
	v_cvt_pk_bf16_f32 v216, v130, v131
	v_cvt_pk_bf16_f32 v217, v132, v133

.LBB0_379:
	v_cndmask_b32_e64 v157, 0, 1, s[54:55]
	v_cmp_ne_u32_e64 s[8:9], 1, v157
	s_andn2_b64 vcc, exec, s[54:55]
	s_mov_b64 s[62:63], -1
	s_cbranch_vccnz .LBB0_409
	s_andn2_b64 vcc, exec, s[56:57]
	s_cbranch_vccnz .LBB0_388
	s_andn2_b64 vcc, exec, s[52:53]
	s_cbranch_vccnz .LBB0_385
	v_add_u32_e32 v157, s45, v140
	v_lshl_add_u64 v[172:173], s[22:23], 0, v[160:161]
	v_lshlrev_b32_e32 v192, 1, v157
	v_mov_b32_e32 v193, v139
	v_lshl_add_u64 v[172:173], v[172:173], 0, v[192:193]
	v_cvt_pk_bf16_f32 v218, v130, v131
	v_cvt_pk_bf16_f32 v219, v132, v133
	s_nop 1
	v_permlane16_swap_b32_e32 v216, v218
	v_permlane16_swap_b32_e32 v217, v219
	v_lshl_add_u64 v[226:227], v[224:225], 0, v[172:173]
	global_store_dwordx4 v[226:227], v[216:219], off
	s_and_saveexec_b64 s[62:63], s[0:1]
	s_cbranch_execz .LBB0_384
	v_readlane_b32 s64, v253, 45
	v_readlane_b32 s65, v253, 46
	v_lshlrev_b32_e32 v192, 2, v191
	v_mov_b32_e32 v193, v139
	v_lshl_add_u64 v[172:173], s[64:65], 0, v[168:169]
	v_lshl_add_u64 v[172:173], v[172:173], 0, v[192:193]
	v_lshlrev_b32_e32 v192, 2, v157
	v_lshl_add_u64 v[172:173], v[172:173], 0, v[192:193]
	global_store_dwordx4 v[172:173], v[130:133], off offset:64

.LBB0_388:
	s_andn2_b64 vcc, exec, s[62:63]
	s_cbranch_vccnz .LBB0_391
	v_cndmask_b32_e64 v173, v163, v165, s[6:7]
	v_cndmask_b32_e64 v172, v162, v164, s[6:7]
	v_add_u32_e32 v157, s45, v140
	v_lshl_add_u64 v[172:173], v[172:173], 2, s[90:91]
	v_lshlrev_b32_e32 v192, 2, v157
	v_mov_b32_e32 v193, v139
	v_lshl_add_u64 v[172:173], v[172:173], 0, v[192:193]
	s_andn2_b64 vcc, exec, s[52:53]
	global_store_dwordx4 v[172:173], v[130:133], off offset:64
	s_cbranch_vccnz .LBB0_391
	v_lshl_add_u64 v[172:173], s[20:21], 0, v[160:161]
	v_lshlrev_b32_e32 v192, 1, v157
	v_mov_b32_e32 v193, v139
	v_lshl_add_u64 v[172:173], v[172:173], 0, v[192:193]
	v_cvt_pk_bf16_f32 v218, v130, v131
	v_cvt_pk_bf16_f32 v219, v132, v133
	s_nop 1
	v_permlane16_swap_b32_e32 v216, v218
	v_permlane16_swap_b32_e32 v217, v219
	v_lshl_add_u64 v[226:227], v[224:225], 0, v[172:173]
	global_store_dwordx4 v[226:227], v[216:219], off

.LBB0_397:
	s_andn2_b64 vcc, exec, s[56:57]
	s_cbranch_vccnz .LBB0_405
	s_andn2_b64 vcc, exec, s[52:53]
	s_cbranch_vccnz .LBB0_402
	v_add_u32_e32 v157, s45, v140
	v_lshl_add_u64 v[172:173], s[22:23], 0, v[160:161]
	v_lshlrev_b32_e32 v192, 1, v157
	v_mov_b32_e32 v193, v139
	v_lshl_add_u64 v[172:173], v[172:173], 0, v[192:193]
	v_cvt_pk_bf16_f32 v222, v130, v131
	v_cvt_pk_bf16_f32 v223, v132, v133
	s_nop 1
	v_permlane16_swap_b32_e32 v220, v222
	v_permlane16_swap_b32_e32 v221, v223
	v_lshl_add_u64 v[226:227], v[224:225], 0, v[172:173]
	global_store_dwordx4 v[226:227], v[220:223], off offset:64
	s_and_saveexec_b64 s[2:3], s[0:1]
	s_cbranch_execz .LBB0_401
	v_readlane_b32 s0, v253, 45
	v_readlane_b32 s1, v253, 46
	v_lshlrev_b32_e32 v192, 2, v191
	v_mov_b32_e32 v193, v139
	v_lshl_add_u64 v[172:173], s[0:1], 0, v[168:169]
	v_lshl_add_u64 v[172:173], v[172:173], 0, v[192:193]
	v_lshlrev_b32_e32 v192, 2, v157
	v_lshl_add_u64 v[172:173], v[172:173], 0, v[192:193]
	global_store_dwordx4 v[172:173], v[130:133], off offset:192

.LBB0_405:
	s_andn2_b64 vcc, exec, s[2:3]
	s_cbranch_vccnz .LBB0_408
	v_cndmask_b32_e64 v163, v163, v165, s[6:7]
	v_cndmask_b32_e64 v162, v162, v164, s[6:7]
	v_add_u32_e32 v157, s45, v140
	v_lshl_add_u64 v[162:163], v[162:163], 2, s[90:91]
	v_lshlrev_b32_e32 v164, 2, v157
	v_mov_b32_e32 v165, v139
	v_lshl_add_u64 v[162:163], v[162:163], 0, v[164:165]
	s_andn2_b64 vcc, exec, s[52:53]
	global_store_dwordx4 v[162:163], v[130:133], off offset:192
	s_cbranch_vccnz .LBB0_408
	v_lshl_add_u64 v[160:161], s[20:21], 0, v[160:161]
	v_lshlrev_b32_e32 v162, 1, v157
	v_mov_b32_e32 v163, v139
	v_lshl_add_u64 v[160:161], v[160:161], 0, v[162:163]
	v_cvt_pk_bf16_f32 v222, v130, v131
	v_cvt_pk_bf16_f32 v223, v132, v133
	s_nop 1
	v_permlane16_swap_b32_e32 v220, v222
	v_permlane16_swap_b32_e32 v221, v223
	v_lshl_add_u64 v[226:227], v[224:225], 0, v[160:161]
	global_store_dwordx4 v[226:227], v[220:223], off offset:64

.LBB0_412:
	s_andn2_b64 vcc, exec, s[56:57]
	s_cbranch_vccnz .LBB0_420
	s_andn2_b64 vcc, exec, s[52:53]
	s_cbranch_vccnz .LBB0_417
	v_add_u32_e32 v157, s45, v140
	v_lshl_add_u64 v[172:173], s[22:23], 0, v[160:161]
	v_lshlrev_b32_e32 v192, 1, v157
	v_mov_b32_e32 v193, v139
	v_lshl_add_u64 v[172:173], v[172:173], 0, v[192:193]
	v_cvt_pk_bf16_f32 v220, v130, v131
	v_cvt_pk_bf16_f32 v221, v132, v133
	s_and_saveexec_b64 s[62:63], s[0:1]
	s_cbranch_execz .LBB0_416
	v_readlane_b32 s64, v253, 45
	v_readlane_b32 s65, v253, 46
	v_lshlrev_b32_e32 v192, 2, v191
	v_mov_b32_e32 v193, v139
	v_lshl_add_u64 v[172:173], s[64:65], 0, v[168:169]
	v_lshl_add_u64 v[172:173], v[172:173], 0, v[192:193]
	v_lshlrev_b32_e32 v192, 2, v157
	v_lshl_add_u64 v[172:173], v[172:173], 0, v[192:193]
	global_store_dwordx4 v[172:173], v[130:133], off offset:128

.LBB0_420:
	s_andn2_b64 vcc, exec, s[62:63]
	s_cbranch_vccnz .LBB0_423
	v_cndmask_b32_e64 v173, v163, v165, s[6:7]
	v_cndmask_b32_e64 v172, v162, v164, s[6:7]
	v_add_u32_e32 v157, s45, v140
	v_lshl_add_u64 v[172:173], v[172:173], 2, s[90:91]
	v_lshlrev_b32_e32 v192, 2, v157
	v_mov_b32_e32 v193, v139
	v_lshl_add_u64 v[172:173], v[172:173], 0, v[192:193]
	s_andn2_b64 vcc, exec, s[52:53]
	global_store_dwordx4 v[172:173], v[130:133], off offset:128
	s_cbranch_vccnz .LBB0_423
	v_lshl_add_u64 v[172:173], s[20:21], 0, v[160:161]
	v_lshlrev_b32_e32 v192, 1, v157
	v_mov_b32_e32 v193, v139
	v_lshl_add_u64 v[172:173], v[172:173], 0, v[192:193]
	v_cvt_pk_bf16_f32 v220, v130, v131
	v_cvt_pk_bf16_f32 v221, v132, v133

.LBB0_450:
	v_ashrrev_i32_e32 v119, 31, v118
	s_movk_i32 s8, 0x5ff
	v_cmp_lt_u32_e64 s[8:9], s8, v127
	v_ashrrev_i32_e32 v125, 31, v124
	v_lshlrev_b32_e32 v131, 9, v127
	v_lshlrev_b32_e32 v128, 11, v127
	v_lshlrev_b64 v[156:157], 9, v[118:119]
	s_mov_b64 s[12:13], 0x2a00000
	v_ashrrev_i32_e32 v127, 31, v126
	v_lshlrev_b64 v[132:133], 20, v[124:125]
	v_lshl_add_u64 v[124:125], v[156:157], 0, s[12:13]
	v_lshlrev_b64 v[158:159], 9, v[126:127]
	s_mov_b64 s[12:13], 0x349e000
	v_cndmask_b32_e64 v129, 0, 1, s[54:55]
	v_lshlrev_b64 v[122:123], 10, v[118:119]
	v_lshl_add_u64 v[126:127], v[158:159], 0, s[12:13]
	v_or_b32_e32 v119, s45, v140
	v_cmp_ne_u32_e64 s[12:13], 1, v129
	s_andn2_b64 vcc, exec, s[54:55]
	s_mov_b64 s[64:65], -1
	s_cbranch_vccnz .LBB0_463
	s_andn2_b64 vcc, exec, s[56:57]
	s_cbranch_vccnz .LBB0_459
	s_andn2_b64 vcc, exec, s[52:53]
	s_cbranch_vccnz .LBB0_456
	v_lshl_add_u64 v[160:161], s[22:23], 0, v[122:123]
	v_lshlrev_b32_e32 v162, 1, v119
	v_mov_b32_e32 v163, v139
	v_lshl_add_u64 v[160:161], v[160:161], 0, v[162:163]
	v_cvt_pk_bf16_f32 v216, v114, v115
	v_cvt_pk_bf16_f32 v217, v116, v117
	s_and_saveexec_b64 s[64:65], s[8:9]
	s_cbranch_execz .LBB0_455
	v_readlane_b32 vcc_lo, v253, 45
	v_readlane_b32 vcc_hi, v253, 46
	v_lshlrev_b32_e32 v162, 2, v131
	v_mov_b32_e32 v163, v139
	v_lshl_add_u64 v[160:161], vcc, 0, v[132:133]
	v_lshl_add_u64 v[160:161], v[160:161], 0, v[162:163]
	v_lshlrev_b32_e32 v162, 2, v119
	v_lshl_add_u64 v[160:161], v[160:161], 0, v[162:163]
	global_store_dwordx4 v[160:161], v[114:117], off

.LBB0_459:
	s_andn2_b64 vcc, exec, s[64:65]
	s_cbranch_vccnz .LBB0_462
	v_cndmask_b32_e64 v161, v125, v127, s[6:7]
	v_cndmask_b32_e64 v160, v124, v126, s[6:7]
	v_lshl_add_u64 v[160:161], v[160:161], 2, s[90:91]
	v_lshlrev_b32_e32 v162, 2, v119
	v_mov_b32_e32 v163, v139
	v_lshl_add_u64 v[160:161], v[160:161], 0, v[162:163]
	s_andn2_b64 vcc, exec, s[52:53]
	global_store_dwordx4 v[160:161], v[114:117], off
	s_cbranch_vccnz .LBB0_462
	v_lshl_add_u64 v[160:161], s[20:21], 0, v[122:123]
	v_lshlrev_b32_e32 v162, 1, v119
	v_mov_b32_e32 v163, v139
	v_lshl_add_u64 v[160:161], v[160:161], 0, v[162:163]
	v_cvt_pk_bf16_f32 v216, v114, v115
	v_cvt_pk_bf16_f32 v217, v116, v117

.LBB0_466:
	s_andn2_b64 vcc, exec, s[56:57]
	s_cbranch_vccnz .LBB0_474
	s_andn2_b64 vcc, exec, s[52:53]
	s_cbranch_vccnz .LBB0_471
	v_add_u32_e32 v119, s45, v140
	v_lshl_add_u64 v[158:159], s[22:23], 0, v[122:123]
	v_lshlrev_b32_e32 v160, 1, v119
	v_mov_b32_e32 v161, v139
	v_lshl_add_u64 v[158:159], v[158:159], 0, v[160:161]
	v_cvt_pk_bf16_f32 v218, v114, v115
	v_cvt_pk_bf16_f32 v219, v116, v117
	s_nop 1
	v_permlane16_swap_b32_e32 v216, v218
	v_permlane16_swap_b32_e32 v217, v219
	v_lshl_add_u64 v[226:227], v[224:225], 0, v[158:159]
	global_store_dwordx4 v[226:227], v[216:219], off
	s_and_saveexec_b64 s[64:65], s[8:9]
	s_cbranch_execz .LBB0_470
	v_readlane_b32 vcc_lo, v253, 45
	v_readlane_b32 vcc_hi, v253, 46
	v_lshlrev_b32_e32 v160, 2, v131
	v_mov_b32_e32 v161, v139
	v_lshl_add_u64 v[158:159], vcc, 0, v[132:133]
	v_lshl_add_u64 v[158:159], v[158:159], 0, v[160:161]
	v_lshlrev_b32_e32 v160, 2, v119
	v_lshl_add_u64 v[158:159], v[158:159], 0, v[160:161]
	global_store_dwordx4 v[158:159], v[114:117], off offset:64

.LBB0_474:
	s_andn2_b64 vcc, exec, s[64:65]
	s_cbranch_vccnz .LBB0_477
	v_cndmask_b32_e64 v159, v125, v127, s[6:7]
	v_cndmask_b32_e64 v158, v124, v126, s[6:7]
	v_add_u32_e32 v119, s45, v140
	v_lshl_add_u64 v[158:159], v[158:159], 2, s[90:91]
	v_lshlrev_b32_e32 v160, 2, v119
	v_mov_b32_e32 v161, v139
	v_lshl_add_u64 v[158:159], v[158:159], 0, v[160:161]
	s_andn2_b64 vcc, exec, s[52:53]
	global_store_dwordx4 v[158:159], v[114:117], off offset:64
	s_cbranch_vccnz .LBB0_477
	v_lshl_add_u64 v[158:159], s[20:21], 0, v[122:123]
	v_lshlrev_b32_e32 v160, 1, v119
	v_mov_b32_e32 v161, v139
	v_lshl_add_u64 v[158:159], v[158:159], 0, v[160:161]
	v_cvt_pk_bf16_f32 v218, v114, v115
	v_cvt_pk_bf16_f32 v219, v116, v117
	s_nop 1
	v_permlane16_swap_b32_e32 v216, v218
	v_permlane16_swap_b32_e32 v217, v219
	v_lshl_add_u64 v[226:227], v[224:225], 0, v[158:159]
	global_store_dwordx4 v[226:227], v[216:219], off

.LBB0_483:
	s_andn2_b64 vcc, exec, s[56:57]
	s_cbranch_vccnz .LBB0_491
	s_andn2_b64 vcc, exec, s[52:53]
	s_cbranch_vccnz .LBB0_488
	v_add_u32_e32 v119, s45, v140
	v_lshl_add_u64 v[158:159], s[22:23], 0, v[122:123]
	v_lshlrev_b32_e32 v160, 1, v119
	v_mov_b32_e32 v161, v139
	v_lshl_add_u64 v[158:159], v[158:159], 0, v[160:161]
	v_cvt_pk_bf16_f32 v222, v114, v115
	v_cvt_pk_bf16_f32 v223, v116, v117
	s_nop 1
	v_permlane16_swap_b32_e32 v220, v222
	v_permlane16_swap_b32_e32 v221, v223
	v_lshl_add_u64 v[226:227], v[224:225], 0, v[158:159]
	global_store_dwordx4 v[226:227], v[220:223], off offset:64
	s_and_saveexec_b64 s[10:11], s[8:9]
	s_cbranch_execz .LBB0_487
	v_readlane_b32 s8, v253, 45
	v_readlane_b32 s9, v253, 46
	v_lshlrev_b32_e32 v160, 2, v131
	v_mov_b32_e32 v161, v139
	v_lshl_add_u64 v[158:159], s[8:9], 0, v[132:133]
	v_lshl_add_u64 v[158:159], v[158:159], 0, v[160:161]
	v_lshlrev_b32_e32 v160, 2, v119
	v_lshl_add_u64 v[158:159], v[158:159], 0, v[160:161]
	global_store_dwordx4 v[158:159], v[114:117], off offset:192

.LBB0_491:
	s_andn2_b64 vcc, exec, s[10:11]
	s_cbranch_vccnz .LBB0_494
	v_cndmask_b32_e64 v125, v125, v127, s[6:7]
	v_cndmask_b32_e64 v124, v124, v126, s[6:7]
	v_add_u32_e32 v119, s45, v140
	v_lshl_add_u64 v[124:125], v[124:125], 2, s[90:91]
	v_lshlrev_b32_e32 v126, 2, v119
	v_mov_b32_e32 v127, v139
	v_lshl_add_u64 v[124:125], v[124:125], 0, v[126:127]
	s_andn2_b64 vcc, exec, s[52:53]
	global_store_dwordx4 v[124:125], v[114:117], off offset:192
	s_cbranch_vccnz .LBB0_494
	v_lshl_add_u64 v[122:123], s[20:21], 0, v[122:123]
	v_lshlrev_b32_e32 v124, 1, v119
	v_mov_b32_e32 v125, v139
	v_lshl_add_u64 v[122:123], v[122:123], 0, v[124:125]
	v_cvt_pk_bf16_f32 v222, v114, v115
	v_cvt_pk_bf16_f32 v223, v116, v117
	s_nop 1
	v_permlane16_swap_b32_e32 v220, v222
	v_permlane16_swap_b32_e32 v221, v223
	v_lshl_add_u64 v[226:227], v[224:225], 0, v[122:123]
	global_store_dwordx4 v[226:227], v[220:223], off offset:64

.LBB0_500:
	s_andn2_b64 vcc, exec, s[56:57]
	s_cbranch_vccnz .LBB0_508
	s_andn2_b64 vcc, exec, s[52:53]
	s_cbranch_vccnz .LBB0_505
	v_add_u32_e32 v119, s45, v140
	v_lshl_add_u64 v[158:159], s[22:23], 0, v[122:123]
	v_lshlrev_b32_e32 v160, 1, v119
	v_mov_b32_e32 v161, v139
	v_lshl_add_u64 v[158:159], v[158:159], 0, v[160:161]
	v_cvt_pk_bf16_f32 v220, v114, v115
	v_cvt_pk_bf16_f32 v221, v116, v117
	s_and_saveexec_b64 s[64:65], s[8:9]
	s_cbranch_execz .LBB0_504
	v_readlane_b32 vcc_lo, v253, 45
	v_readlane_b32 vcc_hi, v253, 46
	v_lshlrev_b32_e32 v160, 2, v131
	v_mov_b32_e32 v161, v139
	v_lshl_add_u64 v[158:159], vcc, 0, v[132:133]
	v_lshl_add_u64 v[158:159], v[158:159], 0, v[160:161]
	v_lshlrev_b32_e32 v160, 2, v119
	v_lshl_add_u64 v[158:159], v[158:159], 0, v[160:161]
	global_store_dwordx4 v[158:159], v[114:117], off offset:128

.LBB0_508:
	s_andn2_b64 vcc, exec, s[64:65]
	s_cbranch_vccnz .LBB0_511
	v_cndmask_b32_e64 v159, v125, v127, s[6:7]
	v_cndmask_b32_e64 v158, v124, v126, s[6:7]
	v_add_u32_e32 v119, s45, v140
	v_lshl_add_u64 v[158:159], v[158:159], 2, s[90:91]
	v_lshlrev_b32_e32 v160, 2, v119
	v_mov_b32_e32 v161, v139
	v_lshl_add_u64 v[158:159], v[158:159], 0, v[160:161]
	s_andn2_b64 vcc, exec, s[52:53]
	global_store_dwordx4 v[158:159], v[114:117], off offset:128
	s_cbranch_vccnz .LBB0_511
	v_lshl_add_u64 v[158:159], s[20:21], 0, v[122:123]
	v_lshlrev_b32_e32 v160, 1, v119
	v_mov_b32_e32 v161, v139
	v_lshl_add_u64 v[158:159], v[158:159], 0, v[160:161]
	v_cvt_pk_bf16_f32 v220, v114, v115
	v_cvt_pk_bf16_f32 v221, v116, v117

.LBB0_538:
	v_ashrrev_i32_e32 v105, 31, v104
	s_movk_i32 s8, 0x5ff
	v_cmp_lt_u32_e64 s[8:9], s8, v111
	v_ashrrev_i32_e32 v109, 31, v108
	v_lshlrev_b32_e32 v120, 9, v111
	v_lshlrev_b32_e32 v112, 11, v111
	v_lshlrev_b64 v[116:117], 9, v[104:105]
	s_mov_b64 s[12:13], 0x2a00000
	v_ashrrev_i32_e32 v111, 31, v110
	v_lshlrev_b64 v[114:115], 20, v[108:109]
	v_lshl_add_u64 v[108:109], v[116:117], 0, s[12:13]
	v_lshlrev_b64 v[118:119], 9, v[110:111]
	s_mov_b64 s[12:13], 0x349e000
	v_cndmask_b32_e64 v113, 0, 1, s[54:55]
	v_lshlrev_b64 v[106:107], 10, v[104:105]
	v_lshl_add_u64 v[110:111], v[118:119], 0, s[12:13]
	v_or_b32_e32 v105, s45, v140
	v_cmp_ne_u32_e64 s[12:13], 1, v113
	s_andn2_b64 vcc, exec, s[54:55]
	s_mov_b64 s[64:65], -1
	s_cbranch_vccnz .LBB0_551
	s_andn2_b64 vcc, exec, s[56:57]
	s_cbranch_vccnz .LBB0_547
	s_andn2_b64 vcc, exec, s[52:53]
	s_cbranch_vccnz .LBB0_544
	v_lshl_add_u64 v[122:123], s[22:23], 0, v[106:107]
	v_lshlrev_b32_e32 v124, 1, v105
	v_mov_b32_e32 v125, v139
	v_lshl_add_u64 v[122:123], v[122:123], 0, v[124:125]
	v_cvt_pk_bf16_f32 v216, v98, v99
	v_cvt_pk_bf16_f32 v217, v100, v101
	s_and_saveexec_b64 s[64:65], s[8:9]
	s_cbranch_execz .LBB0_543
	v_readlane_b32 vcc_lo, v253, 45
	v_readlane_b32 vcc_hi, v253, 46
	v_lshlrev_b32_e32 v124, 2, v120
	v_mov_b32_e32 v125, v139
	v_lshl_add_u64 v[122:123], vcc, 0, v[114:115]
	v_lshl_add_u64 v[122:123], v[122:123], 0, v[124:125]
	v_lshlrev_b32_e32 v124, 2, v105
	v_lshl_add_u64 v[122:123], v[122:123], 0, v[124:125]
	global_store_dwordx4 v[122:123], v[98:101], off

.LBB0_547:
	s_andn2_b64 vcc, exec, s[64:65]
	s_cbranch_vccnz .LBB0_550
	v_cndmask_b32_e64 v123, v109, v111, s[6:7]
	v_cndmask_b32_e64 v122, v108, v110, s[6:7]
	v_lshl_add_u64 v[122:123], v[122:123], 2, s[90:91]
	v_lshlrev_b32_e32 v124, 2, v105
	v_mov_b32_e32 v125, v139
	v_lshl_add_u64 v[122:123], v[122:123], 0, v[124:125]
	s_andn2_b64 vcc, exec, s[52:53]
	global_store_dwordx4 v[122:123], v[98:101], off
	s_cbranch_vccnz .LBB0_550
	v_lshl_add_u64 v[122:123], s[20:21], 0, v[106:107]
	v_lshlrev_b32_e32 v124, 1, v105
	v_mov_b32_e32 v125, v139
	v_lshl_add_u64 v[122:123], v[122:123], 0, v[124:125]
	v_cvt_pk_bf16_f32 v216, v98, v99
	v_cvt_pk_bf16_f32 v217, v100, v101

.LBB0_554:
	s_andn2_b64 vcc, exec, s[56:57]
	s_cbranch_vccnz .LBB0_562
	s_andn2_b64 vcc, exec, s[52:53]
	s_cbranch_vccnz .LBB0_559
	v_add_u32_e32 v105, s45, v140
	v_lshl_add_u64 v[118:119], s[22:23], 0, v[106:107]
	v_lshlrev_b32_e32 v122, 1, v105
	v_mov_b32_e32 v123, v139
	v_lshl_add_u64 v[118:119], v[118:119], 0, v[122:123]
	v_cvt_pk_bf16_f32 v218, v98, v99
	v_cvt_pk_bf16_f32 v219, v100, v101
	s_nop 1
	v_permlane16_swap_b32_e32 v216, v218
	v_permlane16_swap_b32_e32 v217, v219
	v_lshl_add_u64 v[226:227], v[224:225], 0, v[118:119]
	global_store_dwordx4 v[226:227], v[216:219], off
	s_and_saveexec_b64 s[64:65], s[8:9]
	s_cbranch_execz .LBB0_558
	v_readlane_b32 vcc_lo, v253, 45
	v_readlane_b32 vcc_hi, v253, 46
	v_lshlrev_b32_e32 v122, 2, v120
	v_mov_b32_e32 v123, v139
	v_lshl_add_u64 v[118:119], vcc, 0, v[114:115]
	v_lshl_add_u64 v[118:119], v[118:119], 0, v[122:123]
	v_lshlrev_b32_e32 v122, 2, v105
	v_lshl_add_u64 v[118:119], v[118:119], 0, v[122:123]
	global_store_dwordx4 v[118:119], v[98:101], off offset:64

.LBB0_562:
	s_andn2_b64 vcc, exec, s[64:65]
	s_cbranch_vccnz .LBB0_565
	v_cndmask_b32_e64 v119, v109, v111, s[6:7]
	v_cndmask_b32_e64 v118, v108, v110, s[6:7]
	v_add_u32_e32 v105, s45, v140
	v_lshl_add_u64 v[118:119], v[118:119], 2, s[90:91]
	v_lshlrev_b32_e32 v122, 2, v105
	v_mov_b32_e32 v123, v139
	v_lshl_add_u64 v[118:119], v[118:119], 0, v[122:123]
	s_andn2_b64 vcc, exec, s[52:53]
	global_store_dwordx4 v[118:119], v[98:101], off offset:64
	s_cbranch_vccnz .LBB0_565
	v_lshl_add_u64 v[118:119], s[20:21], 0, v[106:107]
	v_lshlrev_b32_e32 v122, 1, v105
	v_mov_b32_e32 v123, v139
	v_lshl_add_u64 v[118:119], v[118:119], 0, v[122:123]
	v_cvt_pk_bf16_f32 v218, v98, v99
	v_cvt_pk_bf16_f32 v219, v100, v101
	s_nop 1
	v_permlane16_swap_b32_e32 v216, v218
	v_permlane16_swap_b32_e32 v217, v219
	v_lshl_add_u64 v[226:227], v[224:225], 0, v[118:119]
	global_store_dwordx4 v[226:227], v[216:219], off

.LBB0_571:
	s_andn2_b64 vcc, exec, s[56:57]
	s_cbranch_vccnz .LBB0_579
	s_andn2_b64 vcc, exec, s[52:53]
	s_cbranch_vccnz .LBB0_576
	v_add_u32_e32 v103, s45, v140
	v_lshl_add_u64 v[118:119], s[22:23], 0, v[106:107]
	v_lshlrev_b32_e32 v122, 1, v103
	v_mov_b32_e32 v123, v139
	v_lshl_add_u64 v[118:119], v[118:119], 0, v[122:123]
	v_cvt_pk_bf16_f32 v222, v98, v99
	v_cvt_pk_bf16_f32 v223, v100, v101
	s_nop 1
	v_permlane16_swap_b32_e32 v220, v222
	v_permlane16_swap_b32_e32 v221, v223
	v_lshl_add_u64 v[226:227], v[224:225], 0, v[118:119]
	global_store_dwordx4 v[226:227], v[220:223], off offset:64
	s_and_saveexec_b64 s[10:11], s[8:9]
	s_cbranch_execz .LBB0_575
	v_readlane_b32 s8, v253, 45
	v_readlane_b32 s9, v253, 46
	v_lshlrev_b32_e32 v120, 2, v120
	v_mov_b32_e32 v121, v139
	v_lshl_add_u64 v[118:119], s[8:9], 0, v[114:115]
	v_lshl_add_u64 v[118:119], v[118:119], 0, v[120:121]
	v_lshlrev_b32_e32 v120, 2, v103
	v_lshl_add_u64 v[118:119], v[118:119], 0, v[120:121]
	global_store_dwordx4 v[118:119], v[98:101], off offset:192

.LBB0_579:
	s_andn2_b64 vcc, exec, s[10:11]
	s_cbranch_vccnz .LBB0_582
	v_cndmask_b32_e64 v109, v109, v111, s[6:7]
	v_cndmask_b32_e64 v108, v108, v110, s[6:7]
	v_add_u32_e32 v103, s45, v140
	v_lshl_add_u64 v[108:109], v[108:109], 2, s[90:91]
	v_lshlrev_b32_e32 v110, 2, v103
	v_mov_b32_e32 v111, v139
	v_lshl_add_u64 v[108:109], v[108:109], 0, v[110:111]
	s_andn2_b64 vcc, exec, s[52:53]
	global_store_dwordx4 v[108:109], v[98:101], off offset:192
	s_cbranch_vccnz .LBB0_582
	v_lshl_add_u64 v[106:107], s[20:21], 0, v[106:107]
	v_lshlrev_b32_e32 v108, 1, v103
	v_mov_b32_e32 v109, v139
	v_lshl_add_u64 v[106:107], v[106:107], 0, v[108:109]
	v_cvt_pk_bf16_f32 v222, v98, v99
	v_cvt_pk_bf16_f32 v223, v100, v101
	s_nop 1
	v_permlane16_swap_b32_e32 v220, v222
	v_permlane16_swap_b32_e32 v221, v223
	v_lshl_add_u64 v[226:227], v[224:225], 0, v[106:107]
	global_store_dwordx4 v[226:227], v[220:223], off offset:64

.LBB0_588:
	s_andn2_b64 vcc, exec, s[56:57]
	s_cbranch_vccnz .LBB0_596
	s_andn2_b64 vcc, exec, s[52:53]
	s_cbranch_vccnz .LBB0_593
	v_add_u32_e32 v105, s45, v140
	v_lshl_add_u64 v[118:119], s[22:23], 0, v[106:107]
	v_lshlrev_b32_e32 v122, 1, v105
	v_mov_b32_e32 v123, v139
	v_lshl_add_u64 v[118:119], v[118:119], 0, v[122:123]
	v_cvt_pk_bf16_f32 v220, v98, v99
	v_cvt_pk_bf16_f32 v221, v100, v101
	s_and_saveexec_b64 s[64:65], s[8:9]
	s_cbranch_execz .LBB0_592
	v_readlane_b32 vcc_lo, v253, 45
	v_readlane_b32 vcc_hi, v253, 46
	v_lshlrev_b32_e32 v122, 2, v120
	v_mov_b32_e32 v123, v139
	v_lshl_add_u64 v[118:119], vcc, 0, v[114:115]
	v_lshl_add_u64 v[118:119], v[118:119], 0, v[122:123]
	v_lshlrev_b32_e32 v122, 2, v105
	v_lshl_add_u64 v[118:119], v[118:119], 0, v[122:123]
	global_store_dwordx4 v[118:119], v[98:101], off offset:128

.LBB0_596:
	s_andn2_b64 vcc, exec, s[64:65]
	s_cbranch_vccnz .LBB0_599
	v_cndmask_b32_e64 v119, v109, v111, s[6:7]
	v_cndmask_b32_e64 v118, v108, v110, s[6:7]
	v_add_u32_e32 v105, s45, v140
	v_lshl_add_u64 v[118:119], v[118:119], 2, s[90:91]
	v_lshlrev_b32_e32 v122, 2, v105
	v_mov_b32_e32 v123, v139
	v_lshl_add_u64 v[118:119], v[118:119], 0, v[122:123]
	s_andn2_b64 vcc, exec, s[52:53]
	global_store_dwordx4 v[118:119], v[98:101], off offset:128
	s_cbranch_vccnz .LBB0_599
	v_lshl_add_u64 v[118:119], s[20:21], 0, v[106:107]
	v_lshlrev_b32_e32 v122, 1, v105
	v_mov_b32_e32 v123, v139
	v_lshl_add_u64 v[118:119], v[118:119], 0, v[122:123]
	v_cvt_pk_bf16_f32 v220, v98, v99
	v_cvt_pk_bf16_f32 v221, v100, v101

.LBB0_626:
	v_ashrrev_i32_e32 v89, 31, v88
	s_movk_i32 s8, 0x5ff
	v_ashrrev_i32_e32 v97, 31, v96
	v_lshlrev_b64 v[100:101], 9, v[88:89]
	s_mov_b64 s[12:13], 0x2a00000
	v_ashrrev_i32_e32 v95, 31, v94
	v_cmp_lt_u32_e64 s[8:9], s8, v92
	v_lshlrev_b32_e32 v104, 9, v92
	v_lshlrev_b64 v[98:99], 20, v[96:97]
	v_lshlrev_b32_e32 v96, 11, v92
	v_lshl_add_u64 v[92:93], v[100:101], 0, s[12:13]
	v_lshlrev_b64 v[102:103], 9, v[94:95]
	s_mov_b64 s[12:13], 0x349e000
	v_cndmask_b32_e64 v97, 0, 1, s[54:55]
	v_lshlrev_b64 v[90:91], 10, v[88:89]
	v_lshl_add_u64 v[94:95], v[102:103], 0, s[12:13]
	v_or_b32_e32 v89, s45, v140
	v_cmp_ne_u32_e64 s[12:13], 1, v97
	s_andn2_b64 vcc, exec, s[54:55]
	s_mov_b64 s[64:65], -1
	s_cbranch_vccnz .LBB0_639
	s_andn2_b64 vcc, exec, s[56:57]
	s_cbranch_vccnz .LBB0_635
	s_andn2_b64 vcc, exec, s[52:53]
	s_cbranch_vccnz .LBB0_632
	v_lshl_add_u64 v[106:107], s[22:23], 0, v[90:91]
	v_lshlrev_b32_e32 v108, 1, v89
	v_mov_b32_e32 v109, v139
	v_lshl_add_u64 v[106:107], v[106:107], 0, v[108:109]
	v_cvt_pk_bf16_f32 v216, v82, v83
	v_cvt_pk_bf16_f32 v217, v84, v85
	s_and_saveexec_b64 s[64:65], s[8:9]
	s_cbranch_execz .LBB0_631
	v_readlane_b32 s38, v253, 45
	v_readlane_b32 s39, v253, 46
	v_lshlrev_b32_e32 v108, 2, v104
	v_mov_b32_e32 v109, v139
	v_lshl_add_u64 v[106:107], s[38:39], 0, v[98:99]
	v_lshl_add_u64 v[106:107], v[106:107], 0, v[108:109]
	v_lshlrev_b32_e32 v108, 2, v89
	v_lshl_add_u64 v[106:107], v[106:107], 0, v[108:109]
	global_store_dwordx4 v[106:107], v[82:85], off

.LBB0_635:
	s_andn2_b64 vcc, exec, s[64:65]
	s_cbranch_vccnz .LBB0_638
	v_cndmask_b32_e64 v107, v93, v95, s[6:7]
	v_cndmask_b32_e64 v106, v92, v94, s[6:7]
	v_lshl_add_u64 v[106:107], v[106:107], 2, s[90:91]
	v_lshlrev_b32_e32 v108, 2, v89
	v_mov_b32_e32 v109, v139
	v_lshl_add_u64 v[106:107], v[106:107], 0, v[108:109]
	s_andn2_b64 vcc, exec, s[52:53]
	global_store_dwordx4 v[106:107], v[82:85], off
	s_cbranch_vccnz .LBB0_638
	v_lshl_add_u64 v[106:107], s[20:21], 0, v[90:91]
	v_lshlrev_b32_e32 v108, 1, v89
	v_mov_b32_e32 v109, v139
	v_lshl_add_u64 v[106:107], v[106:107], 0, v[108:109]
	v_cvt_pk_bf16_f32 v216, v82, v83
	v_cvt_pk_bf16_f32 v217, v84, v85

.LBB0_642:
	s_andn2_b64 vcc, exec, s[56:57]
	s_cbranch_vccnz .LBB0_650
	s_andn2_b64 vcc, exec, s[52:53]
	s_cbranch_vccnz .LBB0_647
	v_add_u32_e32 v89, s45, v140
	v_lshl_add_u64 v[102:103], s[22:23], 0, v[90:91]
	v_lshlrev_b32_e32 v106, 1, v89
	v_mov_b32_e32 v107, v139
	v_lshl_add_u64 v[102:103], v[102:103], 0, v[106:107]
	v_cvt_pk_bf16_f32 v218, v82, v83
	v_cvt_pk_bf16_f32 v219, v84, v85
	s_nop 1
	v_permlane16_swap_b32_e32 v216, v218
	v_permlane16_swap_b32_e32 v217, v219
	v_lshl_add_u64 v[226:227], v[224:225], 0, v[102:103]
	global_store_dwordx4 v[226:227], v[216:219], off
	s_and_saveexec_b64 s[64:65], s[8:9]
	s_cbranch_execz .LBB0_646
	v_readlane_b32 s38, v253, 45
	v_readlane_b32 s39, v253, 46
	v_lshlrev_b32_e32 v106, 2, v104
	v_mov_b32_e32 v107, v139
	v_lshl_add_u64 v[102:103], s[38:39], 0, v[98:99]
	v_lshl_add_u64 v[102:103], v[102:103], 0, v[106:107]
	v_lshlrev_b32_e32 v106, 2, v89
	v_lshl_add_u64 v[102:103], v[102:103], 0, v[106:107]
	global_store_dwordx4 v[102:103], v[82:85], off offset:64

.LBB0_650:
	s_andn2_b64 vcc, exec, s[64:65]
	s_cbranch_vccnz .LBB0_653
	v_cndmask_b32_e64 v103, v93, v95, s[6:7]
	v_cndmask_b32_e64 v102, v92, v94, s[6:7]
	v_add_u32_e32 v89, s45, v140
	v_lshl_add_u64 v[102:103], v[102:103], 2, s[90:91]
	v_lshlrev_b32_e32 v106, 2, v89
	v_mov_b32_e32 v107, v139
	v_lshl_add_u64 v[102:103], v[102:103], 0, v[106:107]
	s_andn2_b64 vcc, exec, s[52:53]
	global_store_dwordx4 v[102:103], v[82:85], off offset:64
	s_cbranch_vccnz .LBB0_653
	v_lshl_add_u64 v[102:103], s[20:21], 0, v[90:91]
	v_lshlrev_b32_e32 v106, 1, v89
	v_mov_b32_e32 v107, v139
	v_lshl_add_u64 v[102:103], v[102:103], 0, v[106:107]
	v_cvt_pk_bf16_f32 v218, v82, v83
	v_cvt_pk_bf16_f32 v219, v84, v85
	s_nop 1
	v_permlane16_swap_b32_e32 v216, v218
	v_permlane16_swap_b32_e32 v217, v219
	v_lshl_add_u64 v[226:227], v[224:225], 0, v[102:103]
	global_store_dwordx4 v[226:227], v[216:219], off

.LBB0_659:
	s_andn2_b64 vcc, exec, s[56:57]
	s_cbranch_vccnz .LBB0_667
	s_andn2_b64 vcc, exec, s[52:53]
	s_cbranch_vccnz .LBB0_664
	v_add_u32_e32 v87, s45, v140
	v_lshl_add_u64 v[102:103], s[22:23], 0, v[90:91]
	v_lshlrev_b32_e32 v106, 1, v87
	v_mov_b32_e32 v107, v139
	v_lshl_add_u64 v[102:103], v[102:103], 0, v[106:107]
	v_cvt_pk_bf16_f32 v222, v82, v83
	v_cvt_pk_bf16_f32 v223, v84, v85
	s_nop 1
	v_permlane16_swap_b32_e32 v220, v222
	v_permlane16_swap_b32_e32 v221, v223
	v_lshl_add_u64 v[226:227], v[224:225], 0, v[102:103]
	global_store_dwordx4 v[226:227], v[220:223], off offset:64
	s_and_saveexec_b64 s[10:11], s[8:9]
	s_cbranch_execz .LBB0_663
	v_readlane_b32 s8, v253, 45
	v_readlane_b32 s9, v253, 46
	v_lshlrev_b32_e32 v104, 2, v104
	v_mov_b32_e32 v105, v139
	v_lshl_add_u64 v[102:103], s[8:9], 0, v[98:99]
	v_lshl_add_u64 v[102:103], v[102:103], 0, v[104:105]
	v_lshlrev_b32_e32 v104, 2, v87
	v_lshl_add_u64 v[102:103], v[102:103], 0, v[104:105]
	global_store_dwordx4 v[102:103], v[82:85], off offset:192

.LBB0_667:
	s_andn2_b64 vcc, exec, s[10:11]
	s_cbranch_vccnz .LBB0_670
	v_cndmask_b32_e64 v93, v93, v95, s[6:7]
	v_cndmask_b32_e64 v92, v92, v94, s[6:7]
	v_add_u32_e32 v87, s45, v140
	v_lshl_add_u64 v[92:93], v[92:93], 2, s[90:91]
	v_lshlrev_b32_e32 v94, 2, v87
	v_mov_b32_e32 v95, v139
	v_lshl_add_u64 v[92:93], v[92:93], 0, v[94:95]
	s_andn2_b64 vcc, exec, s[52:53]
	global_store_dwordx4 v[92:93], v[82:85], off offset:192
	s_cbranch_vccnz .LBB0_670
	v_lshl_add_u64 v[90:91], s[20:21], 0, v[90:91]
	v_lshlrev_b32_e32 v92, 1, v87
	v_mov_b32_e32 v93, v139
	v_lshl_add_u64 v[90:91], v[90:91], 0, v[92:93]
	v_cvt_pk_bf16_f32 v222, v82, v83
	v_cvt_pk_bf16_f32 v223, v84, v85
	s_nop 1
	v_permlane16_swap_b32_e32 v220, v222
	v_permlane16_swap_b32_e32 v221, v223
	v_lshl_add_u64 v[226:227], v[224:225], 0, v[90:91]
	global_store_dwordx4 v[226:227], v[220:223], off offset:64

.LBB0_676:
	s_andn2_b64 vcc, exec, s[56:57]
	s_cbranch_vccnz .LBB0_684
	s_andn2_b64 vcc, exec, s[52:53]
	s_cbranch_vccnz .LBB0_681
	v_add_u32_e32 v89, s45, v140
	v_lshl_add_u64 v[102:103], s[22:23], 0, v[90:91]
	v_lshlrev_b32_e32 v106, 1, v89
	v_mov_b32_e32 v107, v139
	v_lshl_add_u64 v[102:103], v[102:103], 0, v[106:107]
	v_cvt_pk_bf16_f32 v220, v82, v83
	v_cvt_pk_bf16_f32 v221, v84, v85
	s_and_saveexec_b64 s[64:65], s[8:9]
	s_cbranch_execz .LBB0_680
	v_readlane_b32 s38, v253, 45
	v_readlane_b32 s39, v253, 46
	v_lshlrev_b32_e32 v106, 2, v104
	v_mov_b32_e32 v107, v139
	v_lshl_add_u64 v[102:103], s[38:39], 0, v[98:99]
	v_lshl_add_u64 v[102:103], v[102:103], 0, v[106:107]
	v_lshlrev_b32_e32 v106, 2, v89
	v_lshl_add_u64 v[102:103], v[102:103], 0, v[106:107]
	global_store_dwordx4 v[102:103], v[82:85], off offset:128

.LBB0_684:
	s_andn2_b64 vcc, exec, s[64:65]
	s_cbranch_vccnz .LBB0_687
	v_cndmask_b32_e64 v103, v93, v95, s[6:7]
	v_cndmask_b32_e64 v102, v92, v94, s[6:7]
	v_add_u32_e32 v89, s45, v140
	v_lshl_add_u64 v[102:103], v[102:103], 2, s[90:91]
	v_lshlrev_b32_e32 v106, 2, v89
	v_mov_b32_e32 v107, v139
	v_lshl_add_u64 v[102:103], v[102:103], 0, v[106:107]
	s_andn2_b64 vcc, exec, s[52:53]
	global_store_dwordx4 v[102:103], v[82:85], off offset:128
	s_cbranch_vccnz .LBB0_687
	v_lshl_add_u64 v[102:103], s[20:21], 0, v[90:91]
	v_lshlrev_b32_e32 v106, 1, v89
	v_mov_b32_e32 v107, v139
	v_lshl_add_u64 v[102:103], v[102:103], 0, v[106:107]
	v_cvt_pk_bf16_f32 v220, v82, v83
	v_cvt_pk_bf16_f32 v221, v84, v85

.LBB0_714:
	v_ashrrev_i32_e32 v71, 31, v70
	s_movk_i32 s8, 0x5ff
	v_cmp_lt_u32_e64 s[8:9], s8, v79
	v_ashrrev_i32_e32 v77, 31, v76
	v_lshlrev_b32_e32 v88, 9, v79
	v_lshlrev_b32_e32 v80, 11, v79
	v_lshlrev_b64 v[84:85], 9, v[70:71]
	s_mov_b64 s[12:13], 0x2a00000
	v_ashrrev_i32_e32 v79, 31, v78
	v_lshlrev_b64 v[82:83], 20, v[76:77]
	v_lshl_add_u64 v[76:77], v[84:85], 0, s[12:13]
	v_lshlrev_b64 v[86:87], 9, v[78:79]
	s_mov_b64 s[12:13], 0x349e000
	v_cndmask_b32_e64 v81, 0, 1, s[54:55]
	v_lshlrev_b64 v[74:75], 10, v[70:71]
	v_lshl_add_u64 v[78:79], v[86:87], 0, s[12:13]
	v_or_b32_e32 v71, s45, v140
	v_cmp_ne_u32_e64 s[12:13], 1, v81
	s_andn2_b64 vcc, exec, s[54:55]
	s_mov_b64 s[64:65], -1
	s_cbranch_vccnz .LBB0_727
	s_andn2_b64 vcc, exec, s[56:57]
	s_cbranch_vccnz .LBB0_723
	s_andn2_b64 vcc, exec, s[52:53]
	s_cbranch_vccnz .LBB0_720
	v_lshl_add_u64 v[90:91], s[22:23], 0, v[74:75]
	v_lshlrev_b32_e32 v92, 1, v71
	v_mov_b32_e32 v93, v139
	v_lshl_add_u64 v[90:91], v[90:91], 0, v[92:93]
	v_cvt_pk_bf16_f32 v216, v66, v67
	v_cvt_pk_bf16_f32 v217, v68, v69
	s_and_saveexec_b64 s[64:65], s[8:9]
	s_cbranch_execz .LBB0_719
	v_readlane_b32 vcc_lo, v253, 45
	v_readlane_b32 vcc_hi, v253, 46
	v_lshlrev_b32_e32 v92, 2, v88
	v_mov_b32_e32 v93, v139
	v_lshl_add_u64 v[90:91], vcc, 0, v[82:83]
	v_lshl_add_u64 v[90:91], v[90:91], 0, v[92:93]
	v_lshlrev_b32_e32 v92, 2, v71
	v_lshl_add_u64 v[90:91], v[90:91], 0, v[92:93]
	global_store_dwordx4 v[90:91], v[66:69], off

.LBB0_723:
	s_andn2_b64 vcc, exec, s[64:65]
	s_cbranch_vccnz .LBB0_726
	v_cndmask_b32_e64 v91, v77, v79, s[6:7]
	v_cndmask_b32_e64 v90, v76, v78, s[6:7]
	v_lshl_add_u64 v[90:91], v[90:91], 2, s[90:91]
	v_lshlrev_b32_e32 v92, 2, v71
	v_mov_b32_e32 v93, v139
	v_lshl_add_u64 v[90:91], v[90:91], 0, v[92:93]
	s_andn2_b64 vcc, exec, s[52:53]
	global_store_dwordx4 v[90:91], v[66:69], off
	s_cbranch_vccnz .LBB0_726
	v_lshl_add_u64 v[90:91], s[20:21], 0, v[74:75]
	v_lshlrev_b32_e32 v92, 1, v71
	v_mov_b32_e32 v93, v139
	v_lshl_add_u64 v[90:91], v[90:91], 0, v[92:93]
	v_cvt_pk_bf16_f32 v216, v66, v67
	v_cvt_pk_bf16_f32 v217, v68, v69

.LBB0_730:
	s_andn2_b64 vcc, exec, s[56:57]
	s_cbranch_vccnz .LBB0_738
	s_andn2_b64 vcc, exec, s[52:53]
	s_cbranch_vccnz .LBB0_735
	v_add_u32_e32 v71, s45, v140
	v_lshl_add_u64 v[86:87], s[22:23], 0, v[74:75]
	v_lshlrev_b32_e32 v90, 1, v71
	v_mov_b32_e32 v91, v139
	v_lshl_add_u64 v[86:87], v[86:87], 0, v[90:91]
	v_cvt_pk_bf16_f32 v218, v66, v67
	v_cvt_pk_bf16_f32 v219, v68, v69
	s_nop 1
	v_permlane16_swap_b32_e32 v216, v218
	v_permlane16_swap_b32_e32 v217, v219
	v_lshl_add_u64 v[226:227], v[224:225], 0, v[86:87]
	global_store_dwordx4 v[226:227], v[216:219], off
	s_and_saveexec_b64 s[64:65], s[8:9]
	s_cbranch_execz .LBB0_734
	v_readlane_b32 vcc_lo, v253, 45
	v_readlane_b32 vcc_hi, v253, 46
	v_lshlrev_b32_e32 v90, 2, v88
	v_mov_b32_e32 v91, v139
	v_lshl_add_u64 v[86:87], vcc, 0, v[82:83]
	v_lshl_add_u64 v[86:87], v[86:87], 0, v[90:91]
	v_lshlrev_b32_e32 v90, 2, v71
	v_lshl_add_u64 v[86:87], v[86:87], 0, v[90:91]
	global_store_dwordx4 v[86:87], v[66:69], off offset:64

.LBB0_738:
	s_andn2_b64 vcc, exec, s[64:65]
	s_cbranch_vccnz .LBB0_741
	v_cndmask_b32_e64 v87, v77, v79, s[6:7]
	v_cndmask_b32_e64 v86, v76, v78, s[6:7]
	v_add_u32_e32 v71, s45, v140
	v_lshl_add_u64 v[86:87], v[86:87], 2, s[90:91]
	v_lshlrev_b32_e32 v90, 2, v71
	v_mov_b32_e32 v91, v139
	v_lshl_add_u64 v[86:87], v[86:87], 0, v[90:91]
	s_andn2_b64 vcc, exec, s[52:53]
	global_store_dwordx4 v[86:87], v[66:69], off offset:64
	s_cbranch_vccnz .LBB0_741
	v_lshl_add_u64 v[86:87], s[20:21], 0, v[74:75]
	v_lshlrev_b32_e32 v90, 1, v71
	v_mov_b32_e32 v91, v139
	v_lshl_add_u64 v[86:87], v[86:87], 0, v[90:91]
	v_cvt_pk_bf16_f32 v218, v66, v67
	v_cvt_pk_bf16_f32 v219, v68, v69
	s_nop 1
	v_permlane16_swap_b32_e32 v216, v218
	v_permlane16_swap_b32_e32 v217, v219
	v_lshl_add_u64 v[226:227], v[224:225], 0, v[86:87]
	global_store_dwordx4 v[226:227], v[216:219], off

.LBB0_747:
	s_andn2_b64 vcc, exec, s[56:57]
	s_cbranch_vccnz .LBB0_755
	s_andn2_b64 vcc, exec, s[52:53]
	s_cbranch_vccnz .LBB0_752
	v_add_u32_e32 v71, s45, v140
	v_lshl_add_u64 v[86:87], s[22:23], 0, v[74:75]
	v_lshlrev_b32_e32 v90, 1, v71
	v_mov_b32_e32 v91, v139
	v_lshl_add_u64 v[86:87], v[86:87], 0, v[90:91]
	v_cvt_pk_bf16_f32 v222, v66, v67
	v_cvt_pk_bf16_f32 v223, v68, v69
	s_nop 1
	v_permlane16_swap_b32_e32 v220, v222
	v_permlane16_swap_b32_e32 v221, v223
	v_lshl_add_u64 v[226:227], v[224:225], 0, v[86:87]
	global_store_dwordx4 v[226:227], v[220:223], off offset:64
	s_and_saveexec_b64 s[10:11], s[8:9]
	s_cbranch_execz .LBB0_751
	v_readlane_b32 s8, v253, 45
	v_readlane_b32 s9, v253, 46
	v_lshlrev_b32_e32 v88, 2, v88
	v_mov_b32_e32 v89, v139
	v_lshl_add_u64 v[86:87], s[8:9], 0, v[82:83]
	v_lshl_add_u64 v[86:87], v[86:87], 0, v[88:89]
	v_lshlrev_b32_e32 v88, 2, v71
	v_lshl_add_u64 v[86:87], v[86:87], 0, v[88:89]
	global_store_dwordx4 v[86:87], v[66:69], off offset:192

.LBB0_755:
	s_andn2_b64 vcc, exec, s[10:11]
	s_cbranch_vccnz .LBB0_758
	v_cndmask_b32_e64 v77, v77, v79, s[6:7]
	v_cndmask_b32_e64 v76, v76, v78, s[6:7]
	v_add_u32_e32 v71, s45, v140
	v_lshl_add_u64 v[76:77], v[76:77], 2, s[90:91]
	v_lshlrev_b32_e32 v78, 2, v71
	v_mov_b32_e32 v79, v139
	v_lshl_add_u64 v[76:77], v[76:77], 0, v[78:79]
	s_andn2_b64 vcc, exec, s[52:53]
	global_store_dwordx4 v[76:77], v[66:69], off offset:192
	s_cbranch_vccnz .LBB0_758
	v_lshl_add_u64 v[74:75], s[20:21], 0, v[74:75]
	v_lshlrev_b32_e32 v76, 1, v71
	v_mov_b32_e32 v77, v139
	v_lshl_add_u64 v[74:75], v[74:75], 0, v[76:77]
	v_cvt_pk_bf16_f32 v222, v66, v67
	v_cvt_pk_bf16_f32 v223, v68, v69
	s_nop 1
	v_permlane16_swap_b32_e32 v220, v222
	v_permlane16_swap_b32_e32 v221, v223
	v_lshl_add_u64 v[226:227], v[224:225], 0, v[74:75]
	global_store_dwordx4 v[226:227], v[220:223], off offset:64

.LBB0_764:
	s_andn2_b64 vcc, exec, s[56:57]
	s_cbranch_vccnz .LBB0_772
	s_andn2_b64 vcc, exec, s[52:53]
	s_cbranch_vccnz .LBB0_769
	v_add_u32_e32 v71, s45, v140
	v_lshl_add_u64 v[86:87], s[22:23], 0, v[74:75]
	v_lshlrev_b32_e32 v90, 1, v71
	v_mov_b32_e32 v91, v139
	v_lshl_add_u64 v[86:87], v[86:87], 0, v[90:91]
	v_cvt_pk_bf16_f32 v220, v66, v67
	v_cvt_pk_bf16_f32 v221, v68, v69
	s_and_saveexec_b64 s[64:65], s[8:9]
	s_cbranch_execz .LBB0_768
	v_readlane_b32 vcc_lo, v253, 45
	v_readlane_b32 vcc_hi, v253, 46
	v_lshlrev_b32_e32 v90, 2, v88
	v_mov_b32_e32 v91, v139
	v_lshl_add_u64 v[86:87], vcc, 0, v[82:83]
	v_lshl_add_u64 v[86:87], v[86:87], 0, v[90:91]
	v_lshlrev_b32_e32 v90, 2, v71
	v_lshl_add_u64 v[86:87], v[86:87], 0, v[90:91]
	global_store_dwordx4 v[86:87], v[66:69], off offset:128

.LBB0_772:
	s_andn2_b64 vcc, exec, s[64:65]
	s_cbranch_vccnz .LBB0_775
	v_cndmask_b32_e64 v87, v77, v79, s[6:7]
	v_cndmask_b32_e64 v86, v76, v78, s[6:7]
	v_add_u32_e32 v71, s45, v140
	v_lshl_add_u64 v[86:87], v[86:87], 2, s[90:91]
	v_lshlrev_b32_e32 v90, 2, v71
	v_mov_b32_e32 v91, v139
	v_lshl_add_u64 v[86:87], v[86:87], 0, v[90:91]
	s_andn2_b64 vcc, exec, s[52:53]
	global_store_dwordx4 v[86:87], v[66:69], off offset:128
	s_cbranch_vccnz .LBB0_775
	v_lshl_add_u64 v[86:87], s[20:21], 0, v[74:75]
	v_lshlrev_b32_e32 v90, 1, v71
	v_mov_b32_e32 v91, v139
	v_lshl_add_u64 v[86:87], v[86:87], 0, v[90:91]
	v_cvt_pk_bf16_f32 v220, v66, v67
	v_cvt_pk_bf16_f32 v221, v68, v69

.LBB0_802:
	v_ashrrev_i32_e32 v57, 31, v56
	s_movk_i32 s8, 0x5ff
	v_cmp_lt_u32_e64 s[8:9], s8, v63
	v_ashrrev_i32_e32 v61, 31, v60
	v_lshlrev_b32_e32 v72, 9, v63
	v_lshlrev_b32_e32 v64, 11, v63
	v_lshlrev_b64 v[68:69], 9, v[56:57]
	s_mov_b64 s[12:13], 0x2a00000
	v_ashrrev_i32_e32 v63, 31, v62
	v_lshlrev_b64 v[66:67], 20, v[60:61]
	v_lshl_add_u64 v[60:61], v[68:69], 0, s[12:13]
	v_lshlrev_b64 v[70:71], 9, v[62:63]
	s_mov_b64 s[12:13], 0x349e000
	v_cndmask_b32_e64 v65, 0, 1, s[54:55]
	v_lshlrev_b64 v[58:59], 10, v[56:57]
	v_lshl_add_u64 v[62:63], v[70:71], 0, s[12:13]
	v_or_b32_e32 v57, s45, v140
	v_cmp_ne_u32_e64 s[12:13], 1, v65
	s_andn2_b64 vcc, exec, s[54:55]
	s_mov_b64 s[64:65], -1
	s_cbranch_vccnz .LBB0_815
	s_andn2_b64 vcc, exec, s[56:57]
	s_cbranch_vccnz .LBB0_811
	s_andn2_b64 vcc, exec, s[52:53]
	s_cbranch_vccnz .LBB0_808
	v_lshl_add_u64 v[74:75], s[22:23], 0, v[58:59]
	v_lshlrev_b32_e32 v76, 1, v57
	v_mov_b32_e32 v77, v139
	v_lshl_add_u64 v[74:75], v[74:75], 0, v[76:77]
	v_cvt_pk_bf16_f32 v216, v50, v51
	v_cvt_pk_bf16_f32 v217, v52, v53
	s_and_saveexec_b64 s[64:65], s[8:9]
	s_cbranch_execz .LBB0_807
	v_readlane_b32 vcc_lo, v253, 45
	v_readlane_b32 vcc_hi, v253, 46
	v_lshlrev_b32_e32 v76, 2, v72
	v_mov_b32_e32 v77, v139
	v_lshl_add_u64 v[74:75], vcc, 0, v[66:67]
	v_lshl_add_u64 v[74:75], v[74:75], 0, v[76:77]
	v_lshlrev_b32_e32 v76, 2, v57
	v_lshl_add_u64 v[74:75], v[74:75], 0, v[76:77]
	global_store_dwordx4 v[74:75], v[50:53], off

.LBB0_811:
	s_andn2_b64 vcc, exec, s[64:65]
	s_cbranch_vccnz .LBB0_814
	v_cndmask_b32_e64 v75, v61, v63, s[6:7]
	v_cndmask_b32_e64 v74, v60, v62, s[6:7]
	v_lshl_add_u64 v[74:75], v[74:75], 2, s[90:91]
	v_lshlrev_b32_e32 v76, 2, v57
	v_mov_b32_e32 v77, v139
	v_lshl_add_u64 v[74:75], v[74:75], 0, v[76:77]
	s_andn2_b64 vcc, exec, s[52:53]
	global_store_dwordx4 v[74:75], v[50:53], off
	s_cbranch_vccnz .LBB0_814
	v_lshl_add_u64 v[74:75], s[20:21], 0, v[58:59]
	v_lshlrev_b32_e32 v76, 1, v57
	v_mov_b32_e32 v77, v139
	v_lshl_add_u64 v[74:75], v[74:75], 0, v[76:77]
	v_cvt_pk_bf16_f32 v216, v50, v51
	v_cvt_pk_bf16_f32 v217, v52, v53

.LBB0_818:
	s_andn2_b64 vcc, exec, s[56:57]
	s_cbranch_vccnz .LBB0_826
	s_andn2_b64 vcc, exec, s[52:53]
	s_cbranch_vccnz .LBB0_823
	v_add_u32_e32 v57, s45, v140
	v_lshl_add_u64 v[70:71], s[22:23], 0, v[58:59]
	v_lshlrev_b32_e32 v74, 1, v57
	v_mov_b32_e32 v75, v139
	v_lshl_add_u64 v[70:71], v[70:71], 0, v[74:75]
	v_cvt_pk_bf16_f32 v218, v50, v51
	v_cvt_pk_bf16_f32 v219, v52, v53
	s_nop 1
	v_permlane16_swap_b32_e32 v216, v218
	v_permlane16_swap_b32_e32 v217, v219
	v_lshl_add_u64 v[226:227], v[224:225], 0, v[70:71]
	global_store_dwordx4 v[226:227], v[216:219], off
	s_and_saveexec_b64 s[64:65], s[8:9]
	s_cbranch_execz .LBB0_822
	v_readlane_b32 vcc_lo, v253, 45
	v_readlane_b32 vcc_hi, v253, 46
	v_lshlrev_b32_e32 v74, 2, v72
	v_mov_b32_e32 v75, v139
	v_lshl_add_u64 v[70:71], vcc, 0, v[66:67]
	v_lshl_add_u64 v[70:71], v[70:71], 0, v[74:75]
	v_lshlrev_b32_e32 v74, 2, v57
	v_lshl_add_u64 v[70:71], v[70:71], 0, v[74:75]
	global_store_dwordx4 v[70:71], v[50:53], off offset:64

.LBB0_826:
	s_andn2_b64 vcc, exec, s[64:65]
	s_cbranch_vccnz .LBB0_829
	v_cndmask_b32_e64 v71, v61, v63, s[6:7]
	v_cndmask_b32_e64 v70, v60, v62, s[6:7]
	v_add_u32_e32 v57, s45, v140
	v_lshl_add_u64 v[70:71], v[70:71], 2, s[90:91]
	v_lshlrev_b32_e32 v74, 2, v57
	v_mov_b32_e32 v75, v139
	v_lshl_add_u64 v[70:71], v[70:71], 0, v[74:75]
	s_andn2_b64 vcc, exec, s[52:53]
	global_store_dwordx4 v[70:71], v[50:53], off offset:64
	s_cbranch_vccnz .LBB0_829
	v_lshl_add_u64 v[70:71], s[20:21], 0, v[58:59]
	v_lshlrev_b32_e32 v74, 1, v57
	v_mov_b32_e32 v75, v139
	v_lshl_add_u64 v[70:71], v[70:71], 0, v[74:75]
	v_cvt_pk_bf16_f32 v218, v50, v51
	v_cvt_pk_bf16_f32 v219, v52, v53
	s_nop 1
	v_permlane16_swap_b32_e32 v216, v218
	v_permlane16_swap_b32_e32 v217, v219
	v_lshl_add_u64 v[226:227], v[224:225], 0, v[70:71]
	global_store_dwordx4 v[226:227], v[216:219], off

.LBB0_835:
	s_andn2_b64 vcc, exec, s[56:57]
	s_cbranch_vccnz .LBB0_843
	s_andn2_b64 vcc, exec, s[52:53]
	s_cbranch_vccnz .LBB0_840
	v_add_u32_e32 v55, s45, v140
	v_lshl_add_u64 v[70:71], s[22:23], 0, v[58:59]
	v_lshlrev_b32_e32 v74, 1, v55
	v_mov_b32_e32 v75, v139
	v_lshl_add_u64 v[70:71], v[70:71], 0, v[74:75]
	v_cvt_pk_bf16_f32 v222, v50, v51
	v_cvt_pk_bf16_f32 v223, v52, v53
	s_nop 1
	v_permlane16_swap_b32_e32 v220, v222
	v_permlane16_swap_b32_e32 v221, v223
	v_lshl_add_u64 v[226:227], v[224:225], 0, v[70:71]
	global_store_dwordx4 v[226:227], v[220:223], off offset:64
	s_and_saveexec_b64 s[10:11], s[8:9]
	s_cbranch_execz .LBB0_839
	v_readlane_b32 s8, v253, 45
	v_readlane_b32 s9, v253, 46
	v_lshlrev_b32_e32 v72, 2, v72
	v_mov_b32_e32 v73, v139
	v_lshl_add_u64 v[70:71], s[8:9], 0, v[66:67]
	v_lshl_add_u64 v[70:71], v[70:71], 0, v[72:73]
	v_lshlrev_b32_e32 v72, 2, v55
	v_lshl_add_u64 v[70:71], v[70:71], 0, v[72:73]
	global_store_dwordx4 v[70:71], v[50:53], off offset:192

.LBB0_843:
	s_andn2_b64 vcc, exec, s[10:11]
	s_cbranch_vccnz .LBB0_846
	v_cndmask_b32_e64 v61, v61, v63, s[6:7]
	v_cndmask_b32_e64 v60, v60, v62, s[6:7]
	v_add_u32_e32 v55, s45, v140
	v_lshl_add_u64 v[60:61], v[60:61], 2, s[90:91]
	v_lshlrev_b32_e32 v62, 2, v55
	v_mov_b32_e32 v63, v139
	v_lshl_add_u64 v[60:61], v[60:61], 0, v[62:63]
	s_andn2_b64 vcc, exec, s[52:53]
	global_store_dwordx4 v[60:61], v[50:53], off offset:192
	s_cbranch_vccnz .LBB0_846
	v_lshl_add_u64 v[58:59], s[20:21], 0, v[58:59]
	v_lshlrev_b32_e32 v60, 1, v55
	v_mov_b32_e32 v61, v139
	v_lshl_add_u64 v[58:59], v[58:59], 0, v[60:61]
	v_cvt_pk_bf16_f32 v222, v50, v51
	v_cvt_pk_bf16_f32 v223, v52, v53
	s_nop 1
	v_permlane16_swap_b32_e32 v220, v222
	v_permlane16_swap_b32_e32 v221, v223
	v_lshl_add_u64 v[226:227], v[224:225], 0, v[58:59]
	global_store_dwordx4 v[226:227], v[220:223], off offset:64

.LBB0_852:
	s_andn2_b64 vcc, exec, s[56:57]
	s_cbranch_vccnz .LBB0_860
	s_andn2_b64 vcc, exec, s[52:53]
	s_cbranch_vccnz .LBB0_857
	v_add_u32_e32 v57, s45, v140
	v_lshl_add_u64 v[70:71], s[22:23], 0, v[58:59]
	v_lshlrev_b32_e32 v74, 1, v57
	v_mov_b32_e32 v75, v139
	v_lshl_add_u64 v[70:71], v[70:71], 0, v[74:75]
	v_cvt_pk_bf16_f32 v220, v50, v51
	v_cvt_pk_bf16_f32 v221, v52, v53
	s_and_saveexec_b64 s[64:65], s[8:9]
	s_cbranch_execz .LBB0_856
	v_readlane_b32 vcc_lo, v253, 45
	v_readlane_b32 vcc_hi, v253, 46
	v_lshlrev_b32_e32 v74, 2, v72
	v_mov_b32_e32 v75, v139
	v_lshl_add_u64 v[70:71], vcc, 0, v[66:67]
	v_lshl_add_u64 v[70:71], v[70:71], 0, v[74:75]
	v_lshlrev_b32_e32 v74, 2, v57
	v_lshl_add_u64 v[70:71], v[70:71], 0, v[74:75]
	global_store_dwordx4 v[70:71], v[50:53], off offset:128

.LBB0_860:
	s_andn2_b64 vcc, exec, s[64:65]
	s_cbranch_vccnz .LBB0_863
	v_cndmask_b32_e64 v71, v61, v63, s[6:7]
	v_cndmask_b32_e64 v70, v60, v62, s[6:7]
	v_add_u32_e32 v57, s45, v140
	v_lshl_add_u64 v[70:71], v[70:71], 2, s[90:91]
	v_lshlrev_b32_e32 v74, 2, v57
	v_mov_b32_e32 v75, v139
	v_lshl_add_u64 v[70:71], v[70:71], 0, v[74:75]
	s_andn2_b64 vcc, exec, s[52:53]
	global_store_dwordx4 v[70:71], v[50:53], off offset:128
	s_cbranch_vccnz .LBB0_863
	v_lshl_add_u64 v[70:71], s[20:21], 0, v[58:59]
	v_lshlrev_b32_e32 v74, 1, v57
	v_mov_b32_e32 v75, v139
	v_lshl_add_u64 v[70:71], v[70:71], 0, v[74:75]
	v_cvt_pk_bf16_f32 v220, v50, v51
	v_cvt_pk_bf16_f32 v221, v52, v53

.LBB0_890:
	v_ashrrev_i32_e32 v41, 31, v40
	s_movk_i32 s8, 0x5ff
	v_cmp_lt_u32_e64 s[8:9], s8, v47
	v_ashrrev_i32_e32 v45, 31, v44
	v_lshlrev_b32_e32 v56, 9, v47
	v_lshlrev_b32_e32 v48, 11, v47
	v_lshlrev_b64 v[52:53], 9, v[40:41]
	s_mov_b64 s[12:13], 0x2a00000
	v_ashrrev_i32_e32 v47, 31, v46
	v_lshlrev_b64 v[50:51], 20, v[44:45]
	v_lshl_add_u64 v[44:45], v[52:53], 0, s[12:13]
	v_lshlrev_b64 v[54:55], 9, v[46:47]
	s_mov_b64 s[12:13], 0x349e000
	v_cndmask_b32_e64 v49, 0, 1, s[54:55]
	v_lshlrev_b64 v[42:43], 10, v[40:41]
	v_lshl_add_u64 v[46:47], v[54:55], 0, s[12:13]
	v_or_b32_e32 v41, s45, v140
	v_cmp_ne_u32_e64 s[12:13], 1, v49
	s_andn2_b64 vcc, exec, s[54:55]
	s_mov_b64 s[64:65], -1
	s_cbranch_vccnz .LBB0_903
	s_andn2_b64 vcc, exec, s[56:57]
	s_cbranch_vccnz .LBB0_899
	s_andn2_b64 vcc, exec, s[52:53]
	s_cbranch_vccnz .LBB0_896
	v_lshl_add_u64 v[58:59], s[22:23], 0, v[42:43]
	v_lshlrev_b32_e32 v60, 1, v41
	v_mov_b32_e32 v61, v139
	v_lshl_add_u64 v[58:59], v[58:59], 0, v[60:61]
	v_cvt_pk_bf16_f32 v216, v34, v35
	v_cvt_pk_bf16_f32 v217, v36, v37
	s_and_saveexec_b64 s[64:65], s[8:9]
	s_cbranch_execz .LBB0_895
	v_readlane_b32 vcc_lo, v253, 45
	v_readlane_b32 vcc_hi, v253, 46
	v_lshlrev_b32_e32 v60, 2, v56
	v_mov_b32_e32 v61, v139
	v_lshl_add_u64 v[58:59], vcc, 0, v[50:51]
	v_lshl_add_u64 v[58:59], v[58:59], 0, v[60:61]
	v_lshlrev_b32_e32 v60, 2, v41
	v_lshl_add_u64 v[58:59], v[58:59], 0, v[60:61]
	global_store_dwordx4 v[58:59], v[34:37], off

.LBB0_899:
	s_andn2_b64 vcc, exec, s[64:65]
	s_cbranch_vccnz .LBB0_902
	v_cndmask_b32_e64 v59, v45, v47, s[6:7]
	v_cndmask_b32_e64 v58, v44, v46, s[6:7]
	v_lshl_add_u64 v[58:59], v[58:59], 2, s[90:91]
	v_lshlrev_b32_e32 v60, 2, v41
	v_mov_b32_e32 v61, v139
	v_lshl_add_u64 v[58:59], v[58:59], 0, v[60:61]
	s_andn2_b64 vcc, exec, s[52:53]
	global_store_dwordx4 v[58:59], v[34:37], off
	s_cbranch_vccnz .LBB0_902
	v_lshl_add_u64 v[58:59], s[20:21], 0, v[42:43]
	v_lshlrev_b32_e32 v60, 1, v41
	v_mov_b32_e32 v61, v139
	v_lshl_add_u64 v[58:59], v[58:59], 0, v[60:61]
	v_cvt_pk_bf16_f32 v216, v34, v35
	v_cvt_pk_bf16_f32 v217, v36, v37

.LBB0_906:
	s_andn2_b64 vcc, exec, s[56:57]
	s_cbranch_vccnz .LBB0_914
	s_andn2_b64 vcc, exec, s[52:53]
	s_cbranch_vccnz .LBB0_911
	v_add_u32_e32 v41, s45, v140
	v_lshl_add_u64 v[54:55], s[22:23], 0, v[42:43]
	v_lshlrev_b32_e32 v58, 1, v41
	v_mov_b32_e32 v59, v139
	v_lshl_add_u64 v[54:55], v[54:55], 0, v[58:59]
	v_cvt_pk_bf16_f32 v218, v34, v35
	v_cvt_pk_bf16_f32 v219, v36, v37
	s_nop 1
	v_permlane16_swap_b32_e32 v216, v218
	v_permlane16_swap_b32_e32 v217, v219
	v_lshl_add_u64 v[226:227], v[224:225], 0, v[54:55]
	global_store_dwordx4 v[226:227], v[216:219], off
	s_and_saveexec_b64 s[64:65], s[8:9]
	s_cbranch_execz .LBB0_910
	v_readlane_b32 vcc_lo, v253, 45
	v_readlane_b32 vcc_hi, v253, 46
	v_lshlrev_b32_e32 v58, 2, v56
	v_mov_b32_e32 v59, v139
	v_lshl_add_u64 v[54:55], vcc, 0, v[50:51]
	v_lshl_add_u64 v[54:55], v[54:55], 0, v[58:59]
	v_lshlrev_b32_e32 v58, 2, v41
	v_lshl_add_u64 v[54:55], v[54:55], 0, v[58:59]
	global_store_dwordx4 v[54:55], v[34:37], off offset:64

.LBB0_914:
	s_andn2_b64 vcc, exec, s[64:65]
	s_cbranch_vccnz .LBB0_917
	v_cndmask_b32_e64 v55, v45, v47, s[6:7]
	v_cndmask_b32_e64 v54, v44, v46, s[6:7]
	v_add_u32_e32 v41, s45, v140
	v_lshl_add_u64 v[54:55], v[54:55], 2, s[90:91]
	v_lshlrev_b32_e32 v58, 2, v41
	v_mov_b32_e32 v59, v139
	v_lshl_add_u64 v[54:55], v[54:55], 0, v[58:59]
	s_andn2_b64 vcc, exec, s[52:53]
	global_store_dwordx4 v[54:55], v[34:37], off offset:64
	s_cbranch_vccnz .LBB0_917
	v_lshl_add_u64 v[54:55], s[20:21], 0, v[42:43]
	v_lshlrev_b32_e32 v58, 1, v41
	v_mov_b32_e32 v59, v139
	v_lshl_add_u64 v[54:55], v[54:55], 0, v[58:59]
	v_cvt_pk_bf16_f32 v218, v34, v35
	v_cvt_pk_bf16_f32 v219, v36, v37
	s_nop 1
	v_permlane16_swap_b32_e32 v216, v218
	v_permlane16_swap_b32_e32 v217, v219
	v_lshl_add_u64 v[226:227], v[224:225], 0, v[54:55]
	global_store_dwordx4 v[226:227], v[216:219], off

.LBB0_923:
	s_andn2_b64 vcc, exec, s[56:57]
	s_cbranch_vccnz .LBB0_931
	s_andn2_b64 vcc, exec, s[52:53]
	s_cbranch_vccnz .LBB0_928
	v_add_u32_e32 v39, s45, v140
	v_lshl_add_u64 v[54:55], s[22:23], 0, v[42:43]
	v_lshlrev_b32_e32 v58, 1, v39
	v_mov_b32_e32 v59, v139
	v_lshl_add_u64 v[54:55], v[54:55], 0, v[58:59]
	v_cvt_pk_bf16_f32 v222, v34, v35
	v_cvt_pk_bf16_f32 v223, v36, v37
	s_nop 1
	v_permlane16_swap_b32_e32 v220, v222
	v_permlane16_swap_b32_e32 v221, v223
	v_lshl_add_u64 v[226:227], v[224:225], 0, v[54:55]
	global_store_dwordx4 v[226:227], v[220:223], off offset:64
	s_and_saveexec_b64 s[10:11], s[8:9]
	s_cbranch_execz .LBB0_927
	v_readlane_b32 s8, v253, 45
	v_readlane_b32 s9, v253, 46
	v_lshlrev_b32_e32 v56, 2, v56
	v_mov_b32_e32 v57, v139
	v_lshl_add_u64 v[54:55], s[8:9], 0, v[50:51]
	v_lshl_add_u64 v[54:55], v[54:55], 0, v[56:57]
	v_lshlrev_b32_e32 v56, 2, v39
	v_lshl_add_u64 v[54:55], v[54:55], 0, v[56:57]
	global_store_dwordx4 v[54:55], v[34:37], off offset:192

.LBB0_931:
	s_andn2_b64 vcc, exec, s[10:11]
	s_cbranch_vccnz .LBB0_934
	v_cndmask_b32_e64 v45, v45, v47, s[6:7]
	v_cndmask_b32_e64 v44, v44, v46, s[6:7]
	v_add_u32_e32 v39, s45, v140
	v_lshl_add_u64 v[44:45], v[44:45], 2, s[90:91]
	v_lshlrev_b32_e32 v46, 2, v39
	v_mov_b32_e32 v47, v139
	v_lshl_add_u64 v[44:45], v[44:45], 0, v[46:47]
	s_andn2_b64 vcc, exec, s[52:53]
	global_store_dwordx4 v[44:45], v[34:37], off offset:192
	s_cbranch_vccnz .LBB0_934
	v_lshl_add_u64 v[42:43], s[20:21], 0, v[42:43]
	v_lshlrev_b32_e32 v44, 1, v39
	v_mov_b32_e32 v45, v139
	v_lshl_add_u64 v[42:43], v[42:43], 0, v[44:45]
	v_cvt_pk_bf16_f32 v222, v34, v35
	v_cvt_pk_bf16_f32 v223, v36, v37
	s_nop 1
	v_permlane16_swap_b32_e32 v220, v222
	v_permlane16_swap_b32_e32 v221, v223
	v_lshl_add_u64 v[226:227], v[224:225], 0, v[42:43]
	global_store_dwordx4 v[226:227], v[220:223], off offset:64

.LBB0_940:
	s_andn2_b64 vcc, exec, s[56:57]
	s_cbranch_vccnz .LBB0_948
	s_andn2_b64 vcc, exec, s[52:53]
	s_cbranch_vccnz .LBB0_945
	v_add_u32_e32 v41, s45, v140
	v_lshl_add_u64 v[54:55], s[22:23], 0, v[42:43]
	v_lshlrev_b32_e32 v58, 1, v41
	v_mov_b32_e32 v59, v139
	v_lshl_add_u64 v[54:55], v[54:55], 0, v[58:59]
	v_cvt_pk_bf16_f32 v220, v34, v35
	v_cvt_pk_bf16_f32 v221, v36, v37
	s_and_saveexec_b64 s[64:65], s[8:9]
	s_cbranch_execz .LBB0_944
	v_readlane_b32 vcc_lo, v253, 45
	v_readlane_b32 vcc_hi, v253, 46
	v_lshlrev_b32_e32 v58, 2, v56
	v_mov_b32_e32 v59, v139
	v_lshl_add_u64 v[54:55], vcc, 0, v[50:51]
	v_lshl_add_u64 v[54:55], v[54:55], 0, v[58:59]
	v_lshlrev_b32_e32 v58, 2, v41
	v_lshl_add_u64 v[54:55], v[54:55], 0, v[58:59]
	global_store_dwordx4 v[54:55], v[34:37], off offset:128

.LBB0_948:
	s_andn2_b64 vcc, exec, s[64:65]
	s_cbranch_vccnz .LBB0_951
	v_cndmask_b32_e64 v55, v45, v47, s[6:7]
	v_cndmask_b32_e64 v54, v44, v46, s[6:7]
	v_add_u32_e32 v41, s45, v140
	v_lshl_add_u64 v[54:55], v[54:55], 2, s[90:91]
	v_lshlrev_b32_e32 v58, 2, v41
	v_mov_b32_e32 v59, v139
	v_lshl_add_u64 v[54:55], v[54:55], 0, v[58:59]
	s_andn2_b64 vcc, exec, s[52:53]
	global_store_dwordx4 v[54:55], v[34:37], off offset:128
	s_cbranch_vccnz .LBB0_951
	v_lshl_add_u64 v[54:55], s[20:21], 0, v[42:43]
	v_lshlrev_b32_e32 v58, 1, v41
	v_mov_b32_e32 v59, v139
	v_lshl_add_u64 v[54:55], v[54:55], 0, v[58:59]
	v_cvt_pk_bf16_f32 v220, v34, v35
	v_cvt_pk_bf16_f32 v221, v36, v37

.LBB0_978:
	v_ashrrev_i32_e32 v23, 31, v22
	v_ashrrev_i32_e32 v33, 31, v32
	s_movk_i32 s0, 0x5ff
	v_lshlrev_b64 v[34:35], 20, v[32:33]
	v_lshlrev_b64 v[38:39], 9, v[22:23]
	s_mov_b64 s[8:9], 0x2a00000
	v_ashrrev_i32_e32 v31, 31, v30
	v_cndmask_b32_e64 v33, 0, 1, s[54:55]
	v_cmp_lt_u32_e64 s[0:1], s0, v28
	v_lshlrev_b32_e32 v42, 9, v28
	v_lshlrev_b32_e32 v32, 11, v28
	v_lshl_add_u64 v[28:29], v[38:39], 0, s[8:9]
	v_lshlrev_b64 v[40:41], 9, v[30:31]
	s_mov_b64 s[8:9], 0x349e000
	v_cmp_ne_u32_e64 s[10:11], 1, v33
	v_cndmask_b32_e64 v33, 0, 1, s[56:57]
	v_lshlrev_b64 v[26:27], 10, v[22:23]
	v_lshl_add_u64 v[30:31], v[40:41], 0, s[8:9]
	v_or_b32_e32 v23, s45, v140
	s_mov_b64 s[12:13], -1
	s_andn2_b64 vcc, exec, s[54:55]
	v_cmp_ne_u32_e64 s[8:9], 1, v33
	s_cbranch_vccnz .LBB0_991
	s_and_b64 vcc, exec, s[8:9]
	s_cbranch_vccnz .LBB0_987
	s_andn2_b64 vcc, exec, s[52:53]
	s_cbranch_vccnz .LBB0_984
	v_lshl_add_u64 v[44:45], s[22:23], 0, v[26:27]
	v_lshlrev_b32_e32 v138, 1, v23
	v_lshl_add_u64 v[44:45], v[44:45], 0, v[138:139]
	v_cvt_pk_bf16_f32 v216, v18, v19
	v_cvt_pk_bf16_f32 v217, v20, v21
	s_and_saveexec_b64 s[12:13], s[0:1]
	s_cbranch_execz .LBB0_983
	v_readlane_b32 s38, v253, 45
	v_readlane_b32 s39, v253, 46
	v_lshlrev_b32_e32 v138, 2, v42
	s_nop 0
	v_lshl_add_u64 v[44:45], s[38:39], 0, v[34:35]
	v_lshl_add_u64 v[44:45], v[44:45], 0, v[138:139]
	v_lshlrev_b32_e32 v138, 2, v23
	v_lshl_add_u64 v[44:45], v[44:45], 0, v[138:139]
	global_store_dwordx4 v[44:45], v[18:21], off

.LBB0_987:
	s_andn2_b64 vcc, exec, s[12:13]
	s_cbranch_vccnz .LBB0_990
	v_cndmask_b32_e64 v45, v29, v31, s[6:7]
	v_cndmask_b32_e64 v44, v28, v30, s[6:7]
	v_lshl_add_u64 v[44:45], v[44:45], 2, s[90:91]
	v_lshlrev_b32_e32 v138, 2, v23
	v_lshl_add_u64 v[44:45], v[44:45], 0, v[138:139]
	s_andn2_b64 vcc, exec, s[52:53]
	global_store_dwordx4 v[44:45], v[18:21], off
	s_cbranch_vccnz .LBB0_990
	v_lshl_add_u64 v[44:45], s[20:21], 0, v[26:27]
	v_lshlrev_b32_e32 v138, 1, v23
	v_lshl_add_u64 v[44:45], v[44:45], 0, v[138:139]
	v_cvt_pk_bf16_f32 v216, v18, v19
	v_cvt_pk_bf16_f32 v217, v20, v21

.LBB0_994:
	s_and_b64 vcc, exec, s[8:9]
	s_cbranch_vccnz .LBB0_1002
	s_andn2_b64 vcc, exec, s[52:53]
	s_cbranch_vccnz .LBB0_999
	v_add_u32_e32 v23, s45, v140
	v_lshl_add_u64 v[40:41], s[22:23], 0, v[26:27]
	v_lshlrev_b32_e32 v138, 1, v23
	v_lshl_add_u64 v[40:41], v[40:41], 0, v[138:139]
	v_cvt_pk_bf16_f32 v218, v18, v19
	v_cvt_pk_bf16_f32 v219, v20, v21
	s_nop 1
	v_permlane16_swap_b32_e32 v216, v218
	v_permlane16_swap_b32_e32 v217, v219
	v_lshl_add_u64 v[226:227], v[224:225], 0, v[40:41]
	global_store_dwordx4 v[226:227], v[216:219], off
	s_and_saveexec_b64 s[12:13], s[0:1]
	s_cbranch_execz .LBB0_998
	v_readlane_b32 s38, v253, 45
	v_readlane_b32 s39, v253, 46
	v_lshlrev_b32_e32 v138, 2, v42
	s_nop 0
	v_lshl_add_u64 v[40:41], s[38:39], 0, v[34:35]
	v_lshl_add_u64 v[40:41], v[40:41], 0, v[138:139]
	v_lshlrev_b32_e32 v138, 2, v23
	v_lshl_add_u64 v[40:41], v[40:41], 0, v[138:139]
	global_store_dwordx4 v[40:41], v[18:21], off offset:64

.LBB0_1002:
	s_andn2_b64 vcc, exec, s[12:13]
	s_cbranch_vccnz .LBB0_1005
	v_cndmask_b32_e64 v41, v29, v31, s[6:7]
	v_cndmask_b32_e64 v40, v28, v30, s[6:7]
	v_add_u32_e32 v23, s45, v140
	v_lshl_add_u64 v[40:41], v[40:41], 2, s[90:91]
	v_lshlrev_b32_e32 v138, 2, v23
	v_lshl_add_u64 v[40:41], v[40:41], 0, v[138:139]
	s_andn2_b64 vcc, exec, s[52:53]
	global_store_dwordx4 v[40:41], v[18:21], off offset:64
	s_cbranch_vccnz .LBB0_1005
	v_lshl_add_u64 v[40:41], s[20:21], 0, v[26:27]
	v_lshlrev_b32_e32 v138, 1, v23
	v_lshl_add_u64 v[40:41], v[40:41], 0, v[138:139]
	v_cvt_pk_bf16_f32 v218, v18, v19
	v_cvt_pk_bf16_f32 v219, v20, v21
	s_nop 1
	v_permlane16_swap_b32_e32 v216, v218
	v_permlane16_swap_b32_e32 v217, v219
	v_lshl_add_u64 v[226:227], v[224:225], 0, v[40:41]
	global_store_dwordx4 v[226:227], v[216:219], off

.LBB0_1011:
	v_cndmask_b32_e64 v23, 0, 1, s[52:53]
	s_mov_b64 s[10:11], -1
	s_and_b64 vcc, exec, s[8:9]
	v_cmp_ne_u32_e64 s[2:3], 1, v23
	s_cbranch_vccnz .LBB0_1019
	s_and_b64 vcc, exec, s[2:3]
	s_mov_b64 s[8:9], -1
	s_cbranch_vccnz .LBB0_1016
	v_add_u32_e32 v23, s45, v140
	v_lshl_add_u64 v[36:37], s[22:23], 0, v[26:27]
	v_lshlrev_b32_e32 v138, 1, v23
	v_lshl_add_u64 v[36:37], v[36:37], 0, v[138:139]
	v_cvt_pk_bf16_f32 v222, v18, v19
	v_cvt_pk_bf16_f32 v223, v20, v21
	s_nop 1
	v_permlane16_swap_b32_e32 v220, v222
	v_permlane16_swap_b32_e32 v221, v223
	v_lshl_add_u64 v[226:227], v[224:225], 0, v[36:37]
	global_store_dwordx4 v[226:227], v[220:223], off offset:64
	s_and_saveexec_b64 s[8:9], s[0:1]
	s_cbranch_execz .LBB0_1015
	v_readlane_b32 s0, v253, 45
	v_readlane_b32 s1, v253, 46
	v_lshlrev_b32_e32 v138, 2, v42
	s_nop 0
	v_lshl_add_u64 v[36:37], s[0:1], 0, v[34:35]
	v_lshl_add_u64 v[36:37], v[36:37], 0, v[138:139]
	v_lshlrev_b32_e32 v138, 2, v23
	v_lshl_add_u64 v[36:37], v[36:37], 0, v[138:139]
	global_store_dwordx4 v[36:37], v[18:21], off offset:192

.LBB0_1019:
	s_andn2_b64 vcc, exec, s[10:11]
	s_cbranch_vccnz .LBB0_1022
	v_cndmask_b32_e64 v29, v29, v31, s[6:7]
	v_cndmask_b32_e64 v28, v28, v30, s[6:7]
	v_add_u32_e32 v23, s45, v140
	v_lshl_add_u64 v[28:29], v[28:29], 2, s[90:91]
	v_lshlrev_b32_e32 v138, 2, v23
	v_lshl_add_u64 v[28:29], v[28:29], 0, v[138:139]
	s_and_b64 vcc, exec, s[2:3]
	global_store_dwordx4 v[28:29], v[18:21], off offset:192
	s_cbranch_vccnz .LBB0_1022
	v_lshl_add_u64 v[26:27], s[20:21], 0, v[26:27]
	v_lshlrev_b32_e32 v138, 1, v23
	v_lshl_add_u64 v[26:27], v[26:27], 0, v[138:139]
	v_cvt_pk_bf16_f32 v222, v18, v19
	v_cvt_pk_bf16_f32 v223, v20, v21
	s_nop 1
	v_permlane16_swap_b32_e32 v220, v222
	v_permlane16_swap_b32_e32 v221, v223
	v_lshl_add_u64 v[226:227], v[224:225], 0, v[26:27]
	global_store_dwordx4 v[226:227], v[220:223], off offset:64

.LBB0_1028:
	s_and_b64 vcc, exec, s[8:9]
	s_cbranch_vccnz .LBB0_1036
	s_andn2_b64 vcc, exec, s[52:53]
	s_cbranch_vccnz .LBB0_1033
	v_add_u32_e32 v23, s45, v140
	v_lshl_add_u64 v[44:45], s[22:23], 0, v[26:27]
	v_lshlrev_b32_e32 v138, 1, v23
	v_lshl_add_u64 v[44:45], v[44:45], 0, v[138:139]
	v_cvt_pk_bf16_f32 v220, v18, v19
	v_cvt_pk_bf16_f32 v221, v20, v21
	s_and_saveexec_b64 s[12:13], s[0:1]
	s_cbranch_execz .LBB0_1032
	v_readlane_b32 s38, v253, 45
	v_readlane_b32 s39, v253, 46
	v_lshlrev_b32_e32 v138, 2, v42
	s_nop 0
	v_lshl_add_u64 v[44:45], s[38:39], 0, v[34:35]
	v_lshl_add_u64 v[44:45], v[44:45], 0, v[138:139]
	v_lshlrev_b32_e32 v138, 2, v23
	v_lshl_add_u64 v[44:45], v[44:45], 0, v[138:139]
	global_store_dwordx4 v[44:45], v[18:21], off offset:128

.LBB0_1036:
	s_andn2_b64 vcc, exec, s[12:13]
	s_cbranch_vccnz .LBB0_1039
	v_cndmask_b32_e64 v45, v29, v31, s[6:7]
	v_cndmask_b32_e64 v44, v28, v30, s[6:7]
	v_add_u32_e32 v23, s45, v140
	v_lshl_add_u64 v[44:45], v[44:45], 2, s[90:91]
	v_lshlrev_b32_e32 v138, 2, v23
	v_lshl_add_u64 v[44:45], v[44:45], 0, v[138:139]
	s_andn2_b64 vcc, exec, s[52:53]
	global_store_dwordx4 v[44:45], v[18:21], off offset:128
	s_cbranch_vccnz .LBB0_1039
	v_lshl_add_u64 v[44:45], s[20:21], 0, v[26:27]
	v_lshlrev_b32_e32 v138, 1, v23
	v_lshl_add_u64 v[44:45], v[44:45], 0, v[138:139]
	v_cvt_pk_bf16_f32 v220, v18, v19
	v_cvt_pk_bf16_f32 v221, v20, v21
